# attention: output rows staged through LDS and stored as full 128-B lines; unit loop software-pipelined (next unit's q/K,V/ssq2 loads issued in the epilogue, first two tiles wait vmcnt(9) so the previo
# speedup vs baseline: 1.0044x; 1.0044x over previous
; #define INP(k) inptr(k)
; #define WSPTR() kptr(224)
; __device__ __forceinline__ void attn_phase(const Args& a, LAS unsigned char* lds, int layer, int G, int vb) {
;     ...
;     const bf16* proj = (const bf16*)(WSPTR() + WS_PROJ); const bf16* vT = (const bf16*)(WSPTR() + WS_VT); bf16* an = (bf16*)(WSPTR() + WS_MIX); const float* ssq2p = (const float*)(WSPTR() + WS_SSQ2);
;     const float sinkv = INP(8)[layer * 8 + h] * LOG2E;
;     const int ql = lane & 31, hi = lane >> 5;
;     int par = 0;
;     for (int ui = vb; ui < 1024; ui += G, par ^= 1) {
;         const int b = ui & 7, q0 = (ui >> 3) * 32, rowq = b * SEQ + q0;
;         const bf16* qp = proj + (size_t)(rowq + ql) * DIN + h * 64 + 8 * hi;
;         bf16x8 qf[4];
; #pragma unroll
;         for (int kk = 0; kk < 4; ++kk) qf[kk] = *(const bf16x8*)(qp + 16 * kk);
;         float m = sinkv, lsum = 1.0f;
;         f32x16 o0, o1;
; #pragma unroll
;         for (int r = 0; r < 16; ++r) { o0[r] = 0.f; o1[r] = 0.f; }
;         const bf16* vbase = vT + ((size_t)(b * 2 + kvh) * 64 + ql) * SEQ + 4 * hi;
;         const bf16* kbase = proj + (size_t)(b * SEQ + ql) * DIN + 512 + kvh * 64 + 8 * hi;
;         const int rb = ui >> 3, kt_lo = (4 - rb) > 0 ? (4 - rb) : 0, kt_hi = (132 - rb) < 9 ? (132 - rb) : 9;
;         bf16x8 kf[4]; s16x4 vf[2][2][2];
.Lbias_skip:
	v_readlane_b32 s22, v254, 5
	v_readlane_b32 s23, v254, 6
	s_movk_i32 s8, 0xe0
	s_waitcnt lgkmcnt(0)
	s_movk_i32 s7, 0xe0
	s_movk_i32 s6, 0xe0
	s_movk_i32 s5, 0xe0
	s_mov_b32 s4, 64
	s_andn2_b64 vcc, exec, s[22:23]
	s_barrier
	s_cmpk_gt_i32 s33, 0x3ff
	s_cbranch_scc1 .LBB0_686
	s_load_dwordx2 s[4:5], s[0:1], 0xe0
	s_load_dwordx2 s[76:77], s[0:1], 0x40
	v_readfirstlane_b32 s18, v209
	v_and_b32_e32 v160, 63, v209
	s_lshr_b32 s18, s18, 6
	v_and_b32_e32 v2, 31, v160
	v_lshrrev_b32_e32 v3, 5, v160
	s_lshr_b32 s19, s18, 2
	s_and_b32 s22, s18, 3
	s_lshl_b32 s78, s17, 3
	s_add_i32 s78, s78, s18
	s_lshl_b32 s78, s78, 2
	s_waitcnt lgkmcnt(0)
	s_load_dword s45, s[76:77], s78
	v_lshrrev_b32_e32 v161, 3, v160
	v_and_b32_e32 v178, 7, v160
	v_xor_b32_e32 v178, v178, v161
	v_mul_u32_u24_e32 v5, 0xa00, v161
	v_lshl_add_u32 v5, v178, 4, v5
	v_lshrrev_b32_e32 v161, 2, v160
	v_lshlrev_b32_e32 v6, 13, v161
	v_bfe_u32 v178, v160, 4, 2
	v_and_b32_e32 v179, 3, v160
	v_xor_b32_e32 v178, v178, v179
	v_lshl_add_u32 v6, v178, 4, v6
	s_mul_i32 s78, s18, 0x500
	s_add_i32 s78, s78, 0x20890
	v_lshlrev_b32_e32 v161, 4, v3
	v_lshlrev_b32_e32 v178, 2, v2
	v_sub_u32_e32 v7, v161, v178
	v_add_u32_e32 v7, s78, v7
	v_and_b32_e32 v161, 7, v2
	v_lshlrev_b32_e32 v178, 7, v2
	v_or_b32_e32 v179, 0, v3
	v_xor_b32_e32 v179, v179, v161
	v_lshl_add_u32 v142, v179, 4, v178
	v_or_b32_e32 v179, 2, v3
	v_xor_b32_e32 v179, v179, v161
	v_lshl_add_u32 v143, v179, 4, v178
	v_or_b32_e32 v179, 4, v3
	v_xor_b32_e32 v179, v179, v161
	v_lshl_add_u32 v144, v179, 4, v178
	v_or_b32_e32 v179, 6, v3
	v_xor_b32_e32 v179, v179, v161
	v_lshl_add_u32 v145, v179, 4, v178
	v_bfe_u32 v161, v2, 2, 2
	v_lshlrev_b32_e32 v178, 6, v2
	v_lshl_add_u32 v178, v3, 3, v178
	v_add_u32_e32 v178, 0x1000, v178
	v_xor_b32_e32 v179, 0, v161
	v_lshl_add_u32 v146, v179, 4, v178
	v_xor_b32_e32 v179, 1, v161
	v_lshl_add_u32 v147, v179, 4, v178
	v_xor_b32_e32 v179, 2, v161
	v_lshl_add_u32 v148, v179, 4, v178
	v_xor_b32_e32 v179, 3, v161
	v_lshl_add_u32 v149, v179, 4, v178
	v_mul_u32_u24_e32 v180, 0xa00, v2
	v_lshl_add_u32 v180, v3, 4, v180
	v_lshlrev_b32_e32 v181, 19, v3
	v_lshl_add_u32 v181, v2, 4, v181
	v_lshlrev_b32_e32 v182, 11, v2
	v_lshl_add_u32 v182, v3, 3, v182
	s_lshl_b32 s78, s18, 7
	s_add_i32 s78, s78, 10240
	v_lshl_add_u32 v196, v2, 2, s78
	v_lshlrev_b32_e32 v197, 2, v2
	v_add_u32_e32 v197, 10240, v197
	s_mul_i32 s78, s18, 0x1200
	s_add_i32 s78, s78, 0x15000
	v_mul_u32_u24_e32 v40, 0x90, v2
	v_lshl_add_u32 v40, v3, 3, v40
	v_add_u32_e32 v40, s78, v40
	v_lshrrev_b32_e32 v41, 3, v160
	v_and_b32_e32 v42, 7, v160
	v_lshlrev_b32_e32 v42, 4, v42
	v_mul_u32_u24_e32 v43, 0x90, v41
	v_lshl_add_u32 v42, v41, 11, v42
	v_lshrrev_b32_e32 v41, 0, v43
	v_and_b32_e32 v43, 7, v160
	v_lshl_add_u32 v41, v43, 4, v41
	v_add_u32_e32 v41, s78, v41
	s_waitcnt lgkmcnt(0)
	v_mov_b32_e32 v183, 0x3fb8aa3b
	v_mul_f32_e32 v183, s45, v183
	s_mov_b32 s23, s33
	s_mov_b32 s37, 0
	s_lshl_b32 s94, s19, 13
	s_lshl_b32 s95, s22, 10
	s_add_i32 s93, s94, 16384
	s_add_i32 s92, s93, s95
	s_and_b32 s52, s23, 7
	s_lshr_b32 s54, s23, 3
	s_sub_i32 s78, 4, s54
	s_max_i32 s78, s78, 0
	s_sub_i32 s79, 0x84, s54
	s_min_i32 s79, s79, 9
	s_sub_i32 s26, s79, s78
	s_lshl_b32 s55, s52, 12
	s_lshl_b32 s81, s54, 5
	s_add_i32 s55, s55, s81
	s_lshl_b32 s83, s78, 5
	s_add_i32 s83, s83, s81
	s_add_i32 s83, s83, 0xffffff80
	s_lshl_b32 s36, s78, 7
	s_lshl_b32 s85, s52, 12
	s_add_i32 s85, s85, s83
	s_lshl_b32 s87, s22, 3
	s_add_i32 s85, s85, s87
	s_mul_i32 s85, s85, 0xa00
	s_lshl_b32 s87, s19, 7
	s_add_i32 s85, s85, s87
	s_add_i32 s85, s85, 0x400
	s_add_u32 s6, s4, s85
	s_addc_u32 s7, s5, 0
	s_add_u32 s6, s6, 0xd800000
	s_addc_u32 s7, s7, 0
	s_lshl_b32 s85, s52, 1
	s_add_i32 s85, s85, s19
	s_lshl_b32 s85, s85, 6
	s_lshl_b32 s87, s22, 4
	s_add_i32 s85, s85, s87
	s_lshl_b32 s85, s85, 13
	s_lshl_b32 s87, s83, 1
	s_add_i32 s85, s85, s87
	s_add_u32 s8, s4, s85
	s_addc_u32 s9, s5, 0
	s_add_u32 s8, s8, 0x18800000
	s_addc_u32 s9, s9, 0
	s_mul_i32 s85, s55, 0xa00
	s_lshl_b32 s87, s18, 7
	s_add_i32 s85, s85, s87
	s_add_u32 s60, s4, s85
	s_addc_u32 s61, s5, 0
	s_add_u32 s60, s60, 0xd800000
	s_addc_u32 s61, s61, 0
	s_lshl_b32 s85, s55, 4
	s_add_u32 s88, s4, s85
	s_addc_u32 s89, s5, 0
	s_add_u32 s88, s88, 0x1d400000
	s_addc_u32 s89, s89, 0
	s_lshl_b32 s85, s55, 11
	s_add_i32 s85, s85, s87
	s_add_u32 s90, s4, s85
	s_addc_u32 s91, s5, 0
	s_add_u32 s90, s90, 0x12800000
	s_addc_u32 s91, s91, 0
	global_load_dwordx4 v[8:11], v180, s[60:61] offset:0
	global_load_dwordx4 v[12:15], v180, s[60:61] offset:32
	global_load_dwordx4 v[16:19], v180, s[60:61] offset:64
	global_load_dwordx4 v[20:23], v180, s[60:61] offset:96
	global_load_dwordx4 v[210:213], v181, s[88:89]
	s_add_i32 m0, s92, 0
	s_nop 0
	global_load_lds_dwordx4 v5, s[6:7]
	s_add_i32 m0, s92, 4096
	s_add_u32 s6, s6, 0x14000
	s_addc_u32 s7, s7, 0
	global_load_lds_dwordx4 v6, s[8:9]
	s_add_u32 s8, s8, 64
	s_addc_u32 s9, s9, 0
	s_add_i32 m0, s92, 16384
	s_nop 0
	global_load_lds_dwordx4 v5, s[6:7]
	s_add_i32 m0, s92, 20480
	s_add_u32 s6, s6, 0x14000
	s_addc_u32 s7, s7, 0
	global_load_lds_dwordx4 v6, s[8:9]
	s_add_u32 s8, s8, 64
	s_addc_u32 s9, s9, 0
	s_waitcnt vmcnt(0)
; __device__ __forceinline__ void attn_phase(const Args& a, LAS unsigned char* lds, int layer, int G, int vb) {
;     ...
;         float m = sinkv, lsum = 1.0f;
;         f32x16 o0, o1;
; #pragma unroll
;         for (int r = 0; r < 16; ++r) { o0[r] = 0.f; o1[r] = 0.f; }
;         const bf16* vbase = vT + ((size_t)(b * 2 + kvh) * 64 + ql) * SEQ + 4 * hi;
;         const bf16* kbase = proj + (size_t)(b * SEQ + ql) * DIN + 512 + kvh * 64 + 8 * hi;
;         const int rb = ui >> 3, kt_lo = (4 - rb) > 0 ? (4 - rb) : 0, kt_hi = (132 - rb) < 9 ? (132 - rb) : 9;
;         bf16x8 kf[4]; s16x4 vf[2][2][2];
;     ...
;         bf16x8 kg[4]; s16x4 vg[2][2][2];
.Latt_unit:
	v_mov_b32_e32 v140, v183
	v_mov_b32_e32 v141, 1.0
	v_mov_b32_e32 v24, 0
	v_mov_b32_e32 v25, 0
	v_mov_b32_e32 v26, 0
	v_mov_b32_e32 v27, 0
	v_mov_b32_e32 v28, 0
	v_mov_b32_e32 v29, 0
	v_mov_b32_e32 v30, 0
	v_mov_b32_e32 v31, 0
	v_mov_b32_e32 v32, 0
	v_mov_b32_e32 v33, 0
	v_mov_b32_e32 v34, 0
	v_mov_b32_e32 v35, 0
	v_mov_b32_e32 v36, 0
	v_mov_b32_e32 v37, 0
	v_mov_b32_e32 v38, 0
	v_mov_b32_e32 v39, 0
	v_mov_b32_e32 v46, 0
	v_mov_b32_e32 v47, 0
	v_mov_b32_e32 v48, 0
	v_mov_b32_e32 v49, 0
	v_mov_b32_e32 v50, 0
	v_mov_b32_e32 v51, 0
	v_mov_b32_e32 v52, 0
	v_mov_b32_e32 v53, 0
	v_mov_b32_e32 v54, 0
	v_mov_b32_e32 v55, 0
	v_mov_b32_e32 v56, 0
	v_mov_b32_e32 v57, 0
	v_mov_b32_e32 v58, 0
	v_mov_b32_e32 v59, 0
	v_mov_b32_e32 v60, 0
	v_mov_b32_e32 v61, 0
	s_mov_b32 s28, 0
	s_add_i32 s29, s28, 2
	s_and_b32 s29, s29, 3
	s_lshl_b32 s29, s29, 14
	s_add_i32 s29, s29, s92
	s_mov_b32 m0, s29
	s_and_b32 s32, s28, 3
	global_load_lds_dwordx4 v5, s[6:7]
	s_add_i32 m0, s29, 0x1000
	s_add_u32 s6, s6, 0x14000
	s_addc_u32 s7, s7, 0
	global_load_lds_dwordx4 v6, s[8:9]
	s_add_u32 s8, s8, 64
	s_addc_u32 s9, s9, 0
	s_lshl_b32 s32, s32, 14
	s_add_i32 s32, s32, s93
	v_add_u32_e32 v150, s32, v142
	v_add_u32_e32 v151, s32, v143
	v_add_u32_e32 v152, s32, v144
	v_add_u32_e32 v153, s32, v145
	v_add_u32_e32 v154, s32, v146
	v_add_u32_e32 v155, s32, v147
	v_add_u32_e32 v156, s32, v148
	v_add_u32_e32 v158, s32, v149
	v_add_u32_e32 v159, s36, v7
	s_waitcnt vmcnt(9)
	s_barrier
	ds_read2_b32 v[64:65], v159 offset0:0 offset1:1
	ds_read2_b32 v[66:67], v159 offset0:2 offset1:3
	ds_read2_b32 v[68:69], v159 offset0:8 offset1:9
	ds_read2_b32 v[70:71], v159 offset0:10 offset1:11
	ds_read2_b32 v[72:73], v159 offset0:16 offset1:17
	ds_read2_b32 v[74:75], v159 offset0:18 offset1:19
	ds_read2_b32 v[76:77], v159 offset0:24 offset1:25
	ds_read2_b32 v[78:79], v159 offset0:26 offset1:27
	ds_read_b128 v[80:83], v150
	ds_read_b128 v[84:87], v151
	ds_read_b128 v[88:91], v152
	ds_read_b128 v[92:95], v153
	s_add_i32 s36, s36, 0x80
	s_waitcnt lgkmcnt(0)
	v_mfma_f32_32x32x16_bf16 v[64:79], v[80:83], v[8:11], v[64:79]
	v_mfma_f32_32x32x16_bf16 v[64:79], v[84:87], v[12:15], v[64:79]
	v_mfma_f32_32x32x16_bf16 v[64:79], v[88:91], v[16:19], v[64:79]
	v_mfma_f32_32x32x16_bf16 v[64:79], v[92:95], v[20:23], v[64:79]
	ds_read_b64 v[112:113], v154
	ds_read_b64 v[114:115], v155
	ds_read_b64 v[116:117], v156
	ds_read_b64 v[118:119], v158
	ds_read_b64 v[120:121], v154 offset:2048
	ds_read_b64 v[122:123], v155 offset:2048
	ds_read_b64 v[124:125], v156 offset:2048
	ds_read_b64 v[126:127], v158 offset:2048
	s_nop 3
	v_max3_f32 v184, v64, v65, v66
	v_max3_f32 v184, v184, v67, v68
	v_max3_f32 v184, v184, v69, v70
	v_max3_f32 v184, v184, v71, v72
	v_max3_f32 v184, v184, v73, v74
	v_max3_f32 v184, v184, v75, v76
	v_max3_f32 v184, v184, v77, v78
	v_max_f32_e32 v184, v184, v79
	v_mov_b32_e32 v185, v184
	s_nop 1
	v_permlane32_swap_b32_e32 v184, v185
	v_max_f32_e32 v184, v184, v185
	v_cmp_gt_f32_e32 vcc, v184, v140
	s_cbranch_vccz .Latt_norescalep0
	v_max_f32_e32 v185, v140, v184
	v_sub_f32_e32 v186, v140, v185
	v_exp_f32_e32 v186, v186
	v_mov_b32_e32 v140, v185
	v_mov_b32_e32 v187, v1
	v_mul_f32_e32 v141, v141, v186
	v_pk_mul_f32 v[24:25], v[24:25], v[186:187] op_sel_hi:[1,0]
	v_pk_mul_f32 v[26:27], v[26:27], v[186:187] op_sel_hi:[1,0]
	v_pk_mul_f32 v[28:29], v[28:29], v[186:187] op_sel_hi:[1,0]
	v_pk_mul_f32 v[30:31], v[30:31], v[186:187] op_sel_hi:[1,0]
	v_pk_mul_f32 v[32:33], v[32:33], v[186:187] op_sel_hi:[1,0]
	v_pk_mul_f32 v[34:35], v[34:35], v[186:187] op_sel_hi:[1,0]
	v_pk_mul_f32 v[36:37], v[36:37], v[186:187] op_sel_hi:[1,0]
	v_pk_mul_f32 v[38:39], v[38:39], v[186:187] op_sel_hi:[1,0]
	v_pk_mul_f32 v[46:47], v[46:47], v[186:187] op_sel_hi:[1,0]
	v_pk_mul_f32 v[48:49], v[48:49], v[186:187] op_sel_hi:[1,0]
	v_pk_mul_f32 v[50:51], v[50:51], v[186:187] op_sel_hi:[1,0]
	v_pk_mul_f32 v[52:53], v[52:53], v[186:187] op_sel_hi:[1,0]
	v_pk_mul_f32 v[54:55], v[54:55], v[186:187] op_sel_hi:[1,0]
	v_pk_mul_f32 v[56:57], v[56:57], v[186:187] op_sel_hi:[1,0]
	v_pk_mul_f32 v[58:59], v[58:59], v[186:187] op_sel_hi:[1,0]
	v_pk_mul_f32 v[60:61], v[60:61], v[186:187] op_sel_hi:[1,0]
.Latt_norescalep0:
	v_sub_f32_e32 v64, v64, v140
	v_sub_f32_e32 v65, v65, v140
	v_sub_f32_e32 v66, v66, v140
	v_sub_f32_e32 v67, v67, v140
	v_sub_f32_e32 v68, v68, v140
	v_sub_f32_e32 v69, v69, v140
	v_sub_f32_e32 v70, v70, v140
	v_sub_f32_e32 v71, v71, v140
	v_sub_f32_e32 v72, v72, v140
	v_sub_f32_e32 v73, v73, v140
	v_sub_f32_e32 v74, v74, v140
	v_sub_f32_e32 v75, v75, v140
	v_sub_f32_e32 v76, v76, v140
	v_sub_f32_e32 v77, v77, v140
	v_sub_f32_e32 v78, v78, v140
	v_sub_f32_e32 v79, v79, v140
	v_exp_f32_e32 v64, v64
	v_exp_f32_e32 v65, v65
	v_exp_f32_e32 v66, v66
	v_exp_f32_e32 v67, v67
	v_exp_f32_e32 v68, v68
	v_exp_f32_e32 v69, v69
	v_exp_f32_e32 v70, v70
	v_exp_f32_e32 v71, v71
	v_exp_f32_e32 v72, v72
	v_exp_f32_e32 v73, v73
	v_exp_f32_e32 v74, v74
	v_exp_f32_e32 v75, v75
	v_exp_f32_e32 v76, v76
	v_exp_f32_e32 v77, v77
	v_exp_f32_e32 v78, v78
	v_exp_f32_e32 v79, v79
	v_add_f32_e32 v188, v64, v65
	v_add_f32_e32 v189, v66, v67
	v_add_f32_e32 v190, v68, v69
	v_add_f32_e32 v191, v70, v71
	v_add_f32_e32 v192, v72, v73
	v_add_f32_e32 v193, v74, v75
	v_add_f32_e32 v194, v76, v77
	v_add_f32_e32 v195, v78, v79
	v_add_f32_e32 v188, v188, v189
	v_add_f32_e32 v189, v190, v191
	v_add_f32_e32 v190, v192, v193
	v_add_f32_e32 v191, v194, v195
	v_add_f32_e32 v188, v188, v189
	v_add_f32_e32 v190, v190, v191
	v_add_f32_e32 v188, v188, v190
	v_mov_b32_e32 v189, v188
	v_cvt_pk_bf16_f32 v128, v64, v65
	v_cvt_pk_bf16_f32 v129, v66, v67
	v_cvt_pk_bf16_f32 v130, v68, v69
	v_cvt_pk_bf16_f32 v131, v70, v71
	v_permlane32_swap_b32_e32 v188, v189
	v_cvt_pk_bf16_f32 v136, v72, v73
	v_cvt_pk_bf16_f32 v137, v74, v75
	v_cvt_pk_bf16_f32 v138, v76, v77
	v_cvt_pk_bf16_f32 v139, v78, v79
	v_add_f32_e32 v188, v188, v189
	v_add_f32_e32 v141, v141, v188
	s_waitcnt lgkmcnt(0)
	v_mfma_f32_32x32x16_bf16 v[24:39], v[112:115], v[128:131], v[24:39]
	v_mfma_f32_32x32x16_bf16 v[46:61], v[120:123], v[128:131], v[46:61]
	v_mfma_f32_32x32x16_bf16 v[24:39], v[116:119], v[136:139], v[24:39]
	v_mfma_f32_32x32x16_bf16 v[46:61], v[124:127], v[136:139], v[46:61]
	s_add_i32 s28, s28, 1
	s_add_i32 s29, s28, 2
	s_and_b32 s29, s29, 3
	s_lshl_b32 s29, s29, 14
	s_add_i32 s29, s29, s92
	s_mov_b32 m0, s29
	s_and_b32 s32, s28, 3
	global_load_lds_dwordx4 v5, s[6:7]
	s_add_i32 m0, s29, 0x1000
	s_add_u32 s6, s6, 0x14000
	s_addc_u32 s7, s7, 0
	global_load_lds_dwordx4 v6, s[8:9]
	s_add_u32 s8, s8, 64
	s_addc_u32 s9, s9, 0
	s_lshl_b32 s32, s32, 14
	s_add_i32 s32, s32, s93
	v_add_u32_e32 v150, s32, v142
	v_add_u32_e32 v151, s32, v143
	v_add_u32_e32 v152, s32, v144
	v_add_u32_e32 v153, s32, v145
	v_add_u32_e32 v154, s32, v146
	v_add_u32_e32 v155, s32, v147
	v_add_u32_e32 v156, s32, v148
	v_add_u32_e32 v158, s32, v149
	v_add_u32_e32 v159, s36, v7
	s_waitcnt vmcnt(9)
	s_barrier
	ds_read2_b32 v[64:65], v159 offset0:0 offset1:1
	ds_read2_b32 v[66:67], v159 offset0:2 offset1:3
	ds_read2_b32 v[68:69], v159 offset0:8 offset1:9
	ds_read2_b32 v[70:71], v159 offset0:10 offset1:11
	ds_read2_b32 v[72:73], v159 offset0:16 offset1:17
	ds_read2_b32 v[74:75], v159 offset0:18 offset1:19
	ds_read2_b32 v[76:77], v159 offset0:24 offset1:25
	ds_read2_b32 v[78:79], v159 offset0:26 offset1:27
	ds_read_b128 v[80:83], v150
	ds_read_b128 v[84:87], v151
	ds_read_b128 v[88:91], v152
	ds_read_b128 v[92:95], v153
	s_add_i32 s36, s36, 0x80
	s_waitcnt lgkmcnt(0)
	v_mfma_f32_32x32x16_bf16 v[64:79], v[80:83], v[8:11], v[64:79]
	v_mfma_f32_32x32x16_bf16 v[64:79], v[84:87], v[12:15], v[64:79]
	v_mfma_f32_32x32x16_bf16 v[64:79], v[88:91], v[16:19], v[64:79]
	v_mfma_f32_32x32x16_bf16 v[64:79], v[92:95], v[20:23], v[64:79]
	ds_read_b64 v[112:113], v154
	ds_read_b64 v[114:115], v155
	ds_read_b64 v[116:117], v156
	ds_read_b64 v[118:119], v158
	ds_read_b64 v[120:121], v154 offset:2048
	ds_read_b64 v[122:123], v155 offset:2048
	ds_read_b64 v[124:125], v156 offset:2048
	ds_read_b64 v[126:127], v158 offset:2048
	s_nop 3
	v_max3_f32 v184, v64, v65, v66
	v_max3_f32 v184, v184, v67, v68
	v_max3_f32 v184, v184, v69, v70
	v_max3_f32 v184, v184, v71, v72
	v_max3_f32 v184, v184, v73, v74
	v_max3_f32 v184, v184, v75, v76
	v_max3_f32 v184, v184, v77, v78
	v_max_f32_e32 v184, v184, v79
	v_mov_b32_e32 v185, v184
	s_nop 1
	v_permlane32_swap_b32_e32 v184, v185
	v_max_f32_e32 v184, v184, v185
	v_cmp_gt_f32_e32 vcc, v184, v140
	s_cbranch_vccz .Latt_norescalep1
	v_max_f32_e32 v185, v140, v184
	v_sub_f32_e32 v186, v140, v185
	v_exp_f32_e32 v186, v186
	v_mov_b32_e32 v140, v185
	v_mov_b32_e32 v187, v1
	v_mul_f32_e32 v141, v141, v186
	v_pk_mul_f32 v[24:25], v[24:25], v[186:187] op_sel_hi:[1,0]
	v_pk_mul_f32 v[26:27], v[26:27], v[186:187] op_sel_hi:[1,0]
	v_pk_mul_f32 v[28:29], v[28:29], v[186:187] op_sel_hi:[1,0]
	v_pk_mul_f32 v[30:31], v[30:31], v[186:187] op_sel_hi:[1,0]
	v_pk_mul_f32 v[32:33], v[32:33], v[186:187] op_sel_hi:[1,0]
	v_pk_mul_f32 v[34:35], v[34:35], v[186:187] op_sel_hi:[1,0]
	v_pk_mul_f32 v[36:37], v[36:37], v[186:187] op_sel_hi:[1,0]
	v_pk_mul_f32 v[38:39], v[38:39], v[186:187] op_sel_hi:[1,0]
	v_pk_mul_f32 v[46:47], v[46:47], v[186:187] op_sel_hi:[1,0]
	v_pk_mul_f32 v[48:49], v[48:49], v[186:187] op_sel_hi:[1,0]
	v_pk_mul_f32 v[50:51], v[50:51], v[186:187] op_sel_hi:[1,0]
	v_pk_mul_f32 v[52:53], v[52:53], v[186:187] op_sel_hi:[1,0]
	v_pk_mul_f32 v[54:55], v[54:55], v[186:187] op_sel_hi:[1,0]
	v_pk_mul_f32 v[56:57], v[56:57], v[186:187] op_sel_hi:[1,0]
	v_pk_mul_f32 v[58:59], v[58:59], v[186:187] op_sel_hi:[1,0]
	v_pk_mul_f32 v[60:61], v[60:61], v[186:187] op_sel_hi:[1,0]
.Latt_norescalep1:
	v_sub_f32_e32 v64, v64, v140
	v_sub_f32_e32 v65, v65, v140
	v_sub_f32_e32 v66, v66, v140
	v_sub_f32_e32 v67, v67, v140
	v_sub_f32_e32 v68, v68, v140
	v_sub_f32_e32 v69, v69, v140
	v_sub_f32_e32 v70, v70, v140
	v_sub_f32_e32 v71, v71, v140
	v_sub_f32_e32 v72, v72, v140
	v_sub_f32_e32 v73, v73, v140
	v_sub_f32_e32 v74, v74, v140
	v_sub_f32_e32 v75, v75, v140
	v_sub_f32_e32 v76, v76, v140
	v_sub_f32_e32 v77, v77, v140
	v_sub_f32_e32 v78, v78, v140
	v_sub_f32_e32 v79, v79, v140
	v_exp_f32_e32 v64, v64
	v_exp_f32_e32 v65, v65
	v_exp_f32_e32 v66, v66
	v_exp_f32_e32 v67, v67
	v_exp_f32_e32 v68, v68
	v_exp_f32_e32 v69, v69
	v_exp_f32_e32 v70, v70
	v_exp_f32_e32 v71, v71
	v_exp_f32_e32 v72, v72
	v_exp_f32_e32 v73, v73
	v_exp_f32_e32 v74, v74
	v_exp_f32_e32 v75, v75
	v_exp_f32_e32 v76, v76
	v_exp_f32_e32 v77, v77
	v_exp_f32_e32 v78, v78
	v_exp_f32_e32 v79, v79
	v_add_f32_e32 v188, v64, v65
	v_add_f32_e32 v189, v66, v67
	v_add_f32_e32 v190, v68, v69
	v_add_f32_e32 v191, v70, v71
	v_add_f32_e32 v192, v72, v73
	v_add_f32_e32 v193, v74, v75
	v_add_f32_e32 v194, v76, v77
	v_add_f32_e32 v195, v78, v79
	v_add_f32_e32 v188, v188, v189
	v_add_f32_e32 v189, v190, v191
	v_add_f32_e32 v190, v192, v193
	v_add_f32_e32 v191, v194, v195
	v_add_f32_e32 v188, v188, v189
	v_add_f32_e32 v190, v190, v191
	v_add_f32_e32 v188, v188, v190
	v_mov_b32_e32 v189, v188
	v_cvt_pk_bf16_f32 v128, v64, v65
	v_cvt_pk_bf16_f32 v129, v66, v67
	v_cvt_pk_bf16_f32 v130, v68, v69
	v_cvt_pk_bf16_f32 v131, v70, v71
	v_permlane32_swap_b32_e32 v188, v189
	v_cvt_pk_bf16_f32 v136, v72, v73
	v_cvt_pk_bf16_f32 v137, v74, v75
	v_cvt_pk_bf16_f32 v138, v76, v77
	v_cvt_pk_bf16_f32 v139, v78, v79
	v_add_f32_e32 v188, v188, v189
	v_add_f32_e32 v141, v141, v188
	s_waitcnt lgkmcnt(0)
	v_mfma_f32_32x32x16_bf16 v[24:39], v[112:115], v[128:131], v[24:39]
	v_mfma_f32_32x32x16_bf16 v[46:61], v[120:123], v[128:131], v[46:61]
	v_mfma_f32_32x32x16_bf16 v[24:39], v[116:119], v[136:139], v[24:39]
	v_mfma_f32_32x32x16_bf16 v[46:61], v[124:127], v[136:139], v[46:61]
	s_add_i32 s28, s28, 1
; __device__ __forceinline__ void attn_phase(const Args& a, LAS unsigned char* lds, int layer, int G, int vb) {
;     ...
;         ATT_LOAD(kf, vf, kt_lo);
;         for (int kt = kt_lo; kt < kt_hi; kt += 2) {
;             { const int ktn = (kt + 1 < kt_hi) ? kt + 1 : kt; ATT_LOAD(kg, vg, ktn); }
;             ATT_TILE(kf, vf, kt);
;             if (kt + 1 < kt_hi) {
;                 { const int ktn = (kt + 2 < kt_hi) ? kt + 2 : kt + 1; ATT_LOAD(kf, vf, ktn); }
;                 ATT_TILE(kg, vg, kt + 1);
;             }
;         }
.Latt_tile:
	s_add_i32 s29, s28, 2
	s_and_b32 s29, s29, 3
	s_lshl_b32 s29, s29, 14
	s_add_i32 s29, s29, s92
	s_mov_b32 m0, s29
	s_and_b32 s32, s28, 3
	global_load_lds_dwordx4 v5, s[6:7]
	s_add_i32 m0, s29, 0x1000
	s_add_u32 s6, s6, 0x14000
	s_addc_u32 s7, s7, 0
	global_load_lds_dwordx4 v6, s[8:9]
	s_add_u32 s8, s8, 64
	s_addc_u32 s9, s9, 0
	s_lshl_b32 s32, s32, 14
	s_add_i32 s32, s32, s93
	v_add_u32_e32 v150, s32, v142
	v_add_u32_e32 v151, s32, v143
	v_add_u32_e32 v152, s32, v144
	v_add_u32_e32 v153, s32, v145
	v_add_u32_e32 v154, s32, v146
	v_add_u32_e32 v155, s32, v147
	v_add_u32_e32 v156, s32, v148
	v_add_u32_e32 v158, s32, v149
	v_add_u32_e32 v159, s36, v7
	s_waitcnt vmcnt(4)
	s_barrier
	ds_read2_b32 v[64:65], v159 offset0:0 offset1:1
	ds_read2_b32 v[66:67], v159 offset0:2 offset1:3
	ds_read2_b32 v[68:69], v159 offset0:8 offset1:9
	ds_read2_b32 v[70:71], v159 offset0:10 offset1:11
	ds_read2_b32 v[72:73], v159 offset0:16 offset1:17
	ds_read2_b32 v[74:75], v159 offset0:18 offset1:19
	ds_read2_b32 v[76:77], v159 offset0:24 offset1:25
	ds_read2_b32 v[78:79], v159 offset0:26 offset1:27
	ds_read_b128 v[80:83], v150
	ds_read_b128 v[84:87], v151
	ds_read_b128 v[88:91], v152
	ds_read_b128 v[92:95], v153
	s_add_i32 s36, s36, 0x80
	s_waitcnt lgkmcnt(0)
	v_mfma_f32_32x32x16_bf16 v[64:79], v[80:83], v[8:11], v[64:79]
	v_mfma_f32_32x32x16_bf16 v[64:79], v[84:87], v[12:15], v[64:79]
	v_mfma_f32_32x32x16_bf16 v[64:79], v[88:91], v[16:19], v[64:79]
	v_mfma_f32_32x32x16_bf16 v[64:79], v[92:95], v[20:23], v[64:79]
	ds_read_b64 v[112:113], v154
	ds_read_b64 v[114:115], v155
	ds_read_b64 v[116:117], v156
	ds_read_b64 v[118:119], v158
	ds_read_b64 v[120:121], v154 offset:2048
	ds_read_b64 v[122:123], v155 offset:2048
	ds_read_b64 v[124:125], v156 offset:2048
	ds_read_b64 v[126:127], v158 offset:2048
	s_nop 3
	v_max3_f32 v184, v64, v65, v66
	v_max3_f32 v184, v184, v67, v68
	v_max3_f32 v184, v184, v69, v70
	v_max3_f32 v184, v184, v71, v72
	v_max3_f32 v184, v184, v73, v74
	v_max3_f32 v184, v184, v75, v76
	v_max3_f32 v184, v184, v77, v78
	v_max_f32_e32 v184, v184, v79
	v_mov_b32_e32 v185, v184
	s_nop 1
	v_permlane32_swap_b32_e32 v184, v185
	v_max_f32_e32 v184, v184, v185
	v_cmp_gt_f32_e32 vcc, v184, v140
	s_cbranch_vccz .Latt_norescale
	v_max_f32_e32 v185, v140, v184
	v_sub_f32_e32 v186, v140, v185
	v_exp_f32_e32 v186, v186
	v_mov_b32_e32 v140, v185
	v_mov_b32_e32 v187, v1
	v_mul_f32_e32 v141, v141, v186
	v_pk_mul_f32 v[24:25], v[24:25], v[186:187] op_sel_hi:[1,0]
	v_pk_mul_f32 v[26:27], v[26:27], v[186:187] op_sel_hi:[1,0]
	v_pk_mul_f32 v[28:29], v[28:29], v[186:187] op_sel_hi:[1,0]
	v_pk_mul_f32 v[30:31], v[30:31], v[186:187] op_sel_hi:[1,0]
	v_pk_mul_f32 v[32:33], v[32:33], v[186:187] op_sel_hi:[1,0]
	v_pk_mul_f32 v[34:35], v[34:35], v[186:187] op_sel_hi:[1,0]
	v_pk_mul_f32 v[36:37], v[36:37], v[186:187] op_sel_hi:[1,0]
	v_pk_mul_f32 v[38:39], v[38:39], v[186:187] op_sel_hi:[1,0]
	v_pk_mul_f32 v[46:47], v[46:47], v[186:187] op_sel_hi:[1,0]
	v_pk_mul_f32 v[48:49], v[48:49], v[186:187] op_sel_hi:[1,0]
	v_pk_mul_f32 v[50:51], v[50:51], v[186:187] op_sel_hi:[1,0]
	v_pk_mul_f32 v[52:53], v[52:53], v[186:187] op_sel_hi:[1,0]
	v_pk_mul_f32 v[54:55], v[54:55], v[186:187] op_sel_hi:[1,0]
	v_pk_mul_f32 v[56:57], v[56:57], v[186:187] op_sel_hi:[1,0]
	v_pk_mul_f32 v[58:59], v[58:59], v[186:187] op_sel_hi:[1,0]
	v_pk_mul_f32 v[60:61], v[60:61], v[186:187] op_sel_hi:[1,0]
.Latt_norescale:
	v_sub_f32_e32 v64, v64, v140
	v_sub_f32_e32 v65, v65, v140
	v_sub_f32_e32 v66, v66, v140
	v_sub_f32_e32 v67, v67, v140
	v_sub_f32_e32 v68, v68, v140
	v_sub_f32_e32 v69, v69, v140
	v_sub_f32_e32 v70, v70, v140
	v_sub_f32_e32 v71, v71, v140
	v_sub_f32_e32 v72, v72, v140
	v_sub_f32_e32 v73, v73, v140
	v_sub_f32_e32 v74, v74, v140
	v_sub_f32_e32 v75, v75, v140
	v_sub_f32_e32 v76, v76, v140
	v_sub_f32_e32 v77, v77, v140
	v_sub_f32_e32 v78, v78, v140
	v_sub_f32_e32 v79, v79, v140
	v_exp_f32_e32 v64, v64
	v_exp_f32_e32 v65, v65
	v_exp_f32_e32 v66, v66
	v_exp_f32_e32 v67, v67
	v_exp_f32_e32 v68, v68
	v_exp_f32_e32 v69, v69
	v_exp_f32_e32 v70, v70
	v_exp_f32_e32 v71, v71
	v_exp_f32_e32 v72, v72
	v_exp_f32_e32 v73, v73
	v_exp_f32_e32 v74, v74
	v_exp_f32_e32 v75, v75
	v_exp_f32_e32 v76, v76
	v_exp_f32_e32 v77, v77
	v_exp_f32_e32 v78, v78
	v_exp_f32_e32 v79, v79
	v_add_f32_e32 v188, v64, v65
	v_add_f32_e32 v189, v66, v67
	v_add_f32_e32 v190, v68, v69
	v_add_f32_e32 v191, v70, v71
	v_add_f32_e32 v192, v72, v73
	v_add_f32_e32 v193, v74, v75
	v_add_f32_e32 v194, v76, v77
	v_add_f32_e32 v195, v78, v79
	v_add_f32_e32 v188, v188, v189
	v_add_f32_e32 v189, v190, v191
	v_add_f32_e32 v190, v192, v193
	v_add_f32_e32 v191, v194, v195
	v_add_f32_e32 v188, v188, v189
	v_add_f32_e32 v190, v190, v191
	v_add_f32_e32 v188, v188, v190
	v_mov_b32_e32 v189, v188
	v_cvt_pk_bf16_f32 v128, v64, v65
	v_cvt_pk_bf16_f32 v129, v66, v67
	v_cvt_pk_bf16_f32 v130, v68, v69
	v_cvt_pk_bf16_f32 v131, v70, v71
	v_permlane32_swap_b32_e32 v188, v189
	v_cvt_pk_bf16_f32 v136, v72, v73
	v_cvt_pk_bf16_f32 v137, v74, v75
	v_cvt_pk_bf16_f32 v138, v76, v77
	v_cvt_pk_bf16_f32 v139, v78, v79
	v_add_f32_e32 v188, v188, v189
	v_add_f32_e32 v141, v141, v188
	s_waitcnt lgkmcnt(0)
	v_mfma_f32_32x32x16_bf16 v[24:39], v[112:115], v[128:131], v[24:39]
	v_mfma_f32_32x32x16_bf16 v[46:61], v[120:123], v[128:131], v[46:61]
	v_mfma_f32_32x32x16_bf16 v[24:39], v[116:119], v[136:139], v[24:39]
	v_mfma_f32_32x32x16_bf16 v[46:61], v[124:127], v[136:139], v[46:61]
	s_add_i32 s28, s28, 1
	s_cmp_lt_i32 s28, s26
	s_cbranch_scc1 .Latt_tile
	s_mov_b64 s[76:77], s[90:91]
	s_add_i32 s23, s23, s20
	s_cmpk_lt_i32 s23, 0x400
	s_cselect_b32 s45, 1, 0
	s_cbranch_scc0 .Latt_nonext1
; #define LAS __attribute__((address_space(3)))
; __device__ __forceinline__ void attn_phase(const Args& a, LAS unsigned char* lds, int layer, int G, int vb) {
;     ...
;     for (int ui = vb; ui < 1024; ui += G, par ^= 1) {
;         const int b = ui & 7, q0 = (ui >> 3) * 32, rowq = b * SEQ + q0;
;         const bf16* qp = proj + (size_t)(rowq + ql) * DIN + h * 64 + 8 * hi;
;         bf16x8 qf[4];
; #pragma unroll
;         for (int kk = 0; kk < 4; ++kk) qf[kk] = *(const bf16x8*)(qp + 16 * kk);
;         float m = sinkv, lsum = 1.0f;
;         f32x16 o0, o1;
; #pragma unroll
;         for (int r = 0; r < 16; ++r) { o0[r] = 0.f; o1[r] = 0.f; }
;         const bf16* vbase = vT + ((size_t)(b * 2 + kvh) * 64 + ql) * SEQ + 4 * hi;
;         const bf16* kbase = proj + (size_t)(b * SEQ + ql) * DIN + 512 + kvh * 64 + 8 * hi;
;         const int rb = ui >> 3, kt_lo = (4 - rb) > 0 ? (4 - rb) : 0, kt_hi = (132 - rb) < 9 ? (132 - rb) : 9;
;         bf16x8 kf[4]; s16x4 vf[2][2][2];
;     ...
;         const float inv = 1.0f / lsum;
;         float ss = 0.f;
; #pragma unroll
;         for (int r = 0; r < 16; ++r) { o0[r] *= inv; o1[r] *= inv; ss += o0[r] * o0[r] + o1[r] * o1[r]; }
;         ss += __shfl_xor(ss, 32);
;         LAS float* rd = red + par * 256;
;         if (hi == 0) rd[h * 32 + ql] = ss;
;         __syncthreads();
	s_and_b32 s52, s23, 7
	s_lshr_b32 s54, s23, 3
	s_sub_i32 s78, 4, s54
	s_max_i32 s78, s78, 0
	s_sub_i32 s79, 0x84, s54
	s_min_i32 s79, s79, 9
	s_sub_i32 s26, s79, s78
	s_lshl_b32 s55, s52, 12
	s_lshl_b32 s81, s54, 5
	s_add_i32 s55, s55, s81
	s_lshl_b32 s83, s78, 5
	s_add_i32 s83, s83, s81
	s_add_i32 s83, s83, 0xffffff80
	s_lshl_b32 s36, s78, 7
	s_lshl_b32 s85, s52, 12
	s_add_i32 s85, s85, s83
	s_lshl_b32 s87, s22, 3
	s_add_i32 s85, s85, s87
	s_mul_i32 s85, s85, 0xa00
	s_lshl_b32 s87, s19, 7
	s_add_i32 s85, s85, s87
	s_add_i32 s85, s85, 0x400
	s_add_u32 s6, s4, s85
	s_addc_u32 s7, s5, 0
	s_add_u32 s6, s6, 0xd800000
	s_addc_u32 s7, s7, 0
	s_lshl_b32 s85, s52, 1
	s_add_i32 s85, s85, s19
	s_lshl_b32 s85, s85, 6
	s_lshl_b32 s87, s22, 4
	s_add_i32 s85, s85, s87
	s_lshl_b32 s85, s85, 13
	s_lshl_b32 s87, s83, 1
	s_add_i32 s85, s85, s87
	s_add_u32 s8, s4, s85
	s_addc_u32 s9, s5, 0
	s_add_u32 s8, s8, 0x18800000
	s_addc_u32 s9, s9, 0
	s_mul_i32 s85, s55, 0xa00
	s_lshl_b32 s87, s18, 7
	s_add_i32 s85, s85, s87
	s_add_u32 s60, s4, s85
	s_addc_u32 s61, s5, 0
	s_add_u32 s60, s60, 0xd800000
	s_addc_u32 s61, s61, 0
	s_lshl_b32 s85, s55, 4
	s_add_u32 s88, s4, s85
	s_addc_u32 s89, s5, 0
	s_add_u32 s88, s88, 0x1d400000
	s_addc_u32 s89, s89, 0
	s_lshl_b32 s85, s55, 11
	s_add_i32 s85, s85, s87
	s_add_u32 s90, s4, s85
	s_addc_u32 s91, s5, 0
	s_add_u32 s90, s90, 0x12800000
	s_addc_u32 s91, s91, 0
	global_load_dwordx4 v[8:11], v180, s[60:61] offset:0
	global_load_dwordx4 v[12:15], v180, s[60:61] offset:32
	global_load_dwordx4 v[16:19], v180, s[60:61] offset:64
	global_load_dwordx4 v[20:23], v180, s[60:61] offset:96
.Latt_nonext1:
	s_nop 11
	v_rcp_f32_e32 v186, v141
	v_mov_b32_e32 v187, v1
	v_fma_f32 v184, -v141, v186, 1.0
	v_fmac_f32_e32 v186, v184, v186
	v_mov_b32_e32 v188, 0
	v_mov_b32_e32 v189, 0
	v_mov_b32_e32 v190, 0
	v_mov_b32_e32 v191, 0
	v_pk_mul_f32 v[24:25], v[24:25], v[186:187] op_sel_hi:[1,0]
	v_pk_mul_f32 v[26:27], v[26:27], v[186:187] op_sel_hi:[1,0]
	v_pk_mul_f32 v[28:29], v[28:29], v[186:187] op_sel_hi:[1,0]
	v_pk_mul_f32 v[30:31], v[30:31], v[186:187] op_sel_hi:[1,0]
	v_pk_mul_f32 v[32:33], v[32:33], v[186:187] op_sel_hi:[1,0]
	v_pk_mul_f32 v[34:35], v[34:35], v[186:187] op_sel_hi:[1,0]
	v_pk_mul_f32 v[36:37], v[36:37], v[186:187] op_sel_hi:[1,0]
	v_pk_mul_f32 v[38:39], v[38:39], v[186:187] op_sel_hi:[1,0]
	v_pk_mul_f32 v[46:47], v[46:47], v[186:187] op_sel_hi:[1,0]
	v_pk_mul_f32 v[48:49], v[48:49], v[186:187] op_sel_hi:[1,0]
	v_pk_mul_f32 v[50:51], v[50:51], v[186:187] op_sel_hi:[1,0]
	v_pk_mul_f32 v[52:53], v[52:53], v[186:187] op_sel_hi:[1,0]
	v_pk_mul_f32 v[54:55], v[54:55], v[186:187] op_sel_hi:[1,0]
	v_pk_mul_f32 v[56:57], v[56:57], v[186:187] op_sel_hi:[1,0]
	v_pk_mul_f32 v[58:59], v[58:59], v[186:187] op_sel_hi:[1,0]
	v_pk_mul_f32 v[60:61], v[60:61], v[186:187] op_sel_hi:[1,0]
	v_fmac_f32_e32 v188, v24, v24
	v_fmac_f32_e32 v189, v25, v25
	v_fmac_f32_e32 v190, v26, v26
	v_fmac_f32_e32 v191, v27, v27
	v_fmac_f32_e32 v188, v28, v28
	v_fmac_f32_e32 v189, v29, v29
	v_fmac_f32_e32 v190, v30, v30
	v_fmac_f32_e32 v191, v31, v31
	v_fmac_f32_e32 v188, v32, v32
	v_fmac_f32_e32 v189, v33, v33
	v_fmac_f32_e32 v190, v34, v34
	v_fmac_f32_e32 v191, v35, v35
	v_fmac_f32_e32 v188, v36, v36
	v_fmac_f32_e32 v189, v37, v37
	v_fmac_f32_e32 v190, v38, v38
	v_fmac_f32_e32 v191, v39, v39
	v_fmac_f32_e32 v188, v46, v46
	v_fmac_f32_e32 v189, v47, v47
	v_fmac_f32_e32 v190, v48, v48
	v_fmac_f32_e32 v191, v49, v49
	v_fmac_f32_e32 v188, v50, v50
	v_fmac_f32_e32 v189, v51, v51
	v_fmac_f32_e32 v190, v52, v52
	v_fmac_f32_e32 v191, v53, v53
	v_fmac_f32_e32 v188, v54, v54
	v_fmac_f32_e32 v189, v55, v55
	v_fmac_f32_e32 v190, v56, v56
	v_fmac_f32_e32 v191, v57, v57
	v_fmac_f32_e32 v188, v58, v58
	v_fmac_f32_e32 v189, v59, v59
	v_fmac_f32_e32 v190, v60, v60
	v_fmac_f32_e32 v191, v61, v61
	v_add_f32_e32 v188, v188, v189
	v_add_f32_e32 v190, v190, v191
	v_add_f32_e32 v188, v188, v190
	v_mov_b32_e32 v189, v188
	v_add_u32_e32 v198, s37, v196
	v_add_u32_e32 v199, s37, v197
	v_permlane32_swap_b32_e32 v188, v189
	v_add_f32_e32 v188, v188, v189
	ds_write_b32 v198, v188
	s_waitcnt vmcnt(4) lgkmcnt(0)
	s_barrier
	s_cmp_eq_u32 s45, 0
	s_cbranch_scc1 .Latt_nonext2
	s_add_i32 m0, s92, 0
	s_nop 0
	global_load_lds_dwordx4 v5, s[6:7]
	s_add_i32 m0, s92, 4096
	s_add_u32 s6, s6, 0x14000
	s_addc_u32 s7, s7, 0
	global_load_lds_dwordx4 v6, s[8:9]
	s_add_u32 s8, s8, 64
	s_addc_u32 s9, s9, 0
	s_add_i32 m0, s92, 16384
	s_nop 0
	global_load_lds_dwordx4 v5, s[6:7]
	s_add_i32 m0, s92, 20480
	s_add_u32 s6, s6, 0x14000
	s_addc_u32 s7, s7, 0
	global_load_lds_dwordx4 v6, s[8:9]
	s_add_u32 s8, s8, 64
	s_addc_u32 s9, s9, 0
; #define LAS __attribute__((address_space(3)))
; __device__ __forceinline__ unsigned pk2(float lo, float hi) { const f32x2 v = {lo, hi}; return __builtin_bit_cast(unsigned, __builtin_convertvector(v, bf16x2_t)); }
; __device__ __forceinline__ void attn_phase(const Args& a, LAS unsigned char* lds, int layer, int G, int vb) {
;     ...
;         ss += __shfl_xor(ss, 32);
;         LAS float* rd = red + par * 256;
;         if (hi == 0) rd[h * 32 + ql] = ss;
;         __syncthreads();
;         float tot = 0.f;
; #pragma unroll
;         for (int hh = 0; hh < 8; ++hh) tot += rd[hh * 32 + ql];
;         const f32x4 sq = *(const f32x4*)(ssq2p + ((size_t)hi * NT + rowq + ql) * 4);
;         float ts = (sq[0] + sq[1]) + (sq[2] + sq[3]); ts += __shfl_xor(ts, 32);
;         const float rstd = __builtin_amdgcn_rsqf(tot * (1.0f / 512.0f) + 1e-6f) * __builtin_amdgcn_sqrtf(ts * (1.0f / 512.0f) + 1e-6f);
;         bf16* op = an + (size_t)(rowq + ql) * 1024 + h * 64 + 4 * hi;
; #pragma unroll
;         for (int g4 = 0; g4 < 4; ++g4) {
;             u32x2 w0, w1;
;             w0.x = pk2(o0[4 * g4] * rstd, o0[4 * g4 + 1] * rstd); w0.y = pk2(o0[4 * g4 + 2] * rstd, o0[4 * g4 + 3] * rstd);
;             w1.x = pk2(o1[4 * g4] * rstd, o1[4 * g4 + 1] * rstd); w1.y = pk2(o1[4 * g4 + 2] * rstd, o1[4 * g4 + 3] * rstd);
;             *(u32x2*)(op + 8 * g4) = w0; *(u32x2*)(op + 32 + 8 * g4) = w1;
;         }
.Latt_nonext2:
	ds_read2_b32 v[200:201], v199 offset0:0 offset1:32
	ds_read2_b32 v[202:203], v199 offset0:64 offset1:96
	ds_read2_b32 v[204:205], v199 offset0:128 offset1:160
	ds_read2_b32 v[206:207], v199 offset0:192 offset1:224
	v_add_f32_e32 v192, v210, v211
	v_add_f32_e32 v193, v212, v213
	s_cmp_eq_u32 s45, 0
	s_cbranch_scc1 .Latt_nonext3
	global_load_dwordx4 v[210:213], v181, s[88:89]
.Latt_nonext3:
	v_add_f32_e32 v192, v192, v193
	v_mov_b32_e32 v193, v192
	s_nop 1
	v_permlane32_swap_b32_e32 v192, v193
	v_add_f32_e32 v192, v192, v193
	v_fmamk_f32 v192, v192, 0x3b000000, v220
	v_sqrt_f32_e32 v192, v192
	s_waitcnt lgkmcnt(0)
	v_add_f32_e32 v200, v200, v201
	v_add_f32_e32 v202, v202, v203
	v_add_f32_e32 v204, v204, v205
	v_add_f32_e32 v206, v206, v207
	v_add_f32_e32 v200, v200, v202
	v_add_f32_e32 v204, v204, v206
	v_add_f32_e32 v200, v200, v204
	v_fmamk_f32 v200, v200, 0x3b000000, v220
	v_rsq_f32_e32 v200, v200
	v_mov_b32_e32 v201, v1
	v_mul_f32_e32 v200, v200, v192
	v_pk_mul_f32 v[24:25], v[24:25], v[200:201] op_sel_hi:[1,0]
	v_pk_mul_f32 v[26:27], v[26:27], v[200:201] op_sel_hi:[1,0]
	v_cvt_pk_bf16_f32 v214, v24, v25
	v_cvt_pk_bf16_f32 v215, v26, v27
	ds_write_b64 v40, v[214:215] offset:0
	v_pk_mul_f32 v[28:29], v[28:29], v[200:201] op_sel_hi:[1,0]
	v_pk_mul_f32 v[30:31], v[30:31], v[200:201] op_sel_hi:[1,0]
	v_cvt_pk_bf16_f32 v216, v28, v29
	v_cvt_pk_bf16_f32 v217, v30, v31
	ds_write_b64 v40, v[216:217] offset:16
	v_pk_mul_f32 v[32:33], v[32:33], v[200:201] op_sel_hi:[1,0]
	v_pk_mul_f32 v[34:35], v[34:35], v[200:201] op_sel_hi:[1,0]
	v_cvt_pk_bf16_f32 v214, v32, v33
	v_cvt_pk_bf16_f32 v215, v34, v35
	ds_write_b64 v40, v[214:215] offset:32
	v_pk_mul_f32 v[36:37], v[36:37], v[200:201] op_sel_hi:[1,0]
	v_pk_mul_f32 v[38:39], v[38:39], v[200:201] op_sel_hi:[1,0]
	v_cvt_pk_bf16_f32 v216, v36, v37
	v_cvt_pk_bf16_f32 v217, v38, v39
	ds_write_b64 v40, v[216:217] offset:48
	v_pk_mul_f32 v[46:47], v[46:47], v[200:201] op_sel_hi:[1,0]
	v_pk_mul_f32 v[48:49], v[48:49], v[200:201] op_sel_hi:[1,0]
	v_cvt_pk_bf16_f32 v214, v46, v47
	v_cvt_pk_bf16_f32 v215, v48, v49
	ds_write_b64 v40, v[214:215] offset:64
	v_pk_mul_f32 v[50:51], v[50:51], v[200:201] op_sel_hi:[1,0]
	v_pk_mul_f32 v[52:53], v[52:53], v[200:201] op_sel_hi:[1,0]
	v_cvt_pk_bf16_f32 v216, v50, v51
	v_cvt_pk_bf16_f32 v217, v52, v53
	ds_write_b64 v40, v[216:217] offset:80
	v_pk_mul_f32 v[54:55], v[54:55], v[200:201] op_sel_hi:[1,0]
	v_pk_mul_f32 v[56:57], v[56:57], v[200:201] op_sel_hi:[1,0]
	v_cvt_pk_bf16_f32 v214, v54, v55
	v_cvt_pk_bf16_f32 v215, v56, v57
	ds_write_b64 v40, v[214:215] offset:96
	v_pk_mul_f32 v[58:59], v[58:59], v[200:201] op_sel_hi:[1,0]
	v_pk_mul_f32 v[60:61], v[60:61], v[200:201] op_sel_hi:[1,0]
	v_cvt_pk_bf16_f32 v216, v58, v59
	v_cvt_pk_bf16_f32 v217, v60, v61
	ds_write_b64 v40, v[216:217] offset:112
	s_waitcnt lgkmcnt(0)
	ds_read_b128 v[24:27], v41 offset:0
	ds_read_b128 v[28:31], v41 offset:1152
	ds_read_b128 v[32:35], v41 offset:2304
	ds_read_b128 v[36:39], v41 offset:3456
	s_waitcnt lgkmcnt(3)
	global_store_dwordx4 v42, v[24:27], s[76:77]
	s_waitcnt lgkmcnt(2)
	s_add_u32 s94, s76, 0x4000
	s_addc_u32 s95, s77, 0
	global_store_dwordx4 v42, v[28:31], s[94:95]
	s_waitcnt lgkmcnt(1)
	s_add_u32 s94, s76, 0x8000
	s_addc_u32 s95, s77, 0
	global_store_dwordx4 v42, v[32:35], s[94:95]
	s_waitcnt lgkmcnt(0)
	s_add_u32 s94, s76, 0xc000
	s_addc_u32 s95, s77, 0
	global_store_dwordx4 v42, v[36:39], s[94:95]
	s_xor_b32 s37, s37, 0x400
	s_cmp_lg_u32 s45, 0
	s_cbranch_scc1 .Latt_unit
